# non-temporal hint on the h stores of the SwiGLU epilogue (keep x resident in the memory-side cache)
# speedup vs baseline: 1.0220x; 1.0001x over previous
.Lep0_fast:
	v_mad_u64_u32 v[174:175], s[10:11], s28, v162, 0
	v_lshl_or_b32 v164, s25, 7, v186
	v_mov_b32_e32 v165, 0
	s_lshl_b64 s[78:79], s[28:29], 5
	s_lshl_b64 s[84:85], s[28:29], 8
	v_lshl_add_u64 v[174:175], v[174:175], 0, v[164:165]
	v_lshl_add_u64 v[174:175], v[174:175], 1, s[70:71]
	v_lshl_add_u64 v[166:167], v[174:175], 0, s[84:85]
	v_mul_f32_e32 v190, v250, v124
	v_mul_f32_e32 v191, v250, v125
	v_mul_f32_e32 v192, v250, v126
	v_mul_f32_e32 v193, v250, v127
	v_mul_f32_e32 v194, v250, v116
	v_mul_f32_e32 v195, v250, v117
	v_mul_f32_e32 v196, v250, v118
	v_mul_f32_e32 v197, v250, v119
	v_exp_f32_e32 v190, v190
	v_exp_f32_e32 v191, v191
	v_exp_f32_e32 v192, v192
	v_exp_f32_e32 v193, v193
	v_exp_f32_e32 v194, v194
	v_exp_f32_e32 v195, v195
	v_exp_f32_e32 v196, v196
	v_exp_f32_e32 v197, v197
	v_mul_f32_e32 v198, v124, v108
	v_mul_f32_e32 v199, v125, v109
	v_mul_f32_e32 v200, v126, v110
	v_mul_f32_e32 v201, v127, v111
	v_mul_f32_e32 v202, v116, v100
	v_mul_f32_e32 v203, v117, v101
	v_mul_f32_e32 v204, v118, v102
	v_mul_f32_e32 v205, v119, v103
	v_fma_f32 v190, v190, v242, v242
	v_fma_f32 v191, v191, v242, v242
	v_fma_f32 v192, v192, v242, v242
	v_fma_f32 v193, v193, v242, v242
	v_fma_f32 v194, v194, v242, v242
	v_fma_f32 v195, v195, v242, v242
	v_fma_f32 v196, v196, v242, v242
	v_fma_f32 v197, v197, v242, v242
	v_rcp_f32_e32 v190, v190
	v_rcp_f32_e32 v191, v191
	v_rcp_f32_e32 v192, v192
	v_rcp_f32_e32 v193, v193
	v_rcp_f32_e32 v194, v194
	v_rcp_f32_e32 v195, v195
	v_rcp_f32_e32 v196, v196
	v_rcp_f32_e32 v197, v197
	s_nop 0
	v_mul_f32_e32 v198, v198, v190
	v_mul_f32_e32 v199, v199, v191
	v_mul_f32_e32 v200, v200, v192
	v_mul_f32_e32 v201, v201, v193
	v_mul_f32_e32 v202, v202, v194
	v_mul_f32_e32 v203, v203, v195
	v_mul_f32_e32 v204, v204, v196
	v_mul_f32_e32 v205, v205, v197
	v_cvt_pk_bf16_f32 v190, v198, v199
	v_cvt_pk_bf16_f32 v191, v200, v201
	v_cvt_pk_bf16_f32 v192, v202, v203
	v_cvt_pk_bf16_f32 v193, v204, v205
	global_store_dwordx4 v[174:175], v[190:193], off nt
	v_lshl_add_u64 v[174:175], v[174:175], 0, s[78:79]
	v_mul_f32_e32 v206, v251, v120
	v_mul_f32_e32 v207, v251, v121
	v_mul_f32_e32 v208, v251, v122
	v_mul_f32_e32 v209, v251, v123
	v_mul_f32_e32 v210, v251, v112
	v_mul_f32_e32 v211, v251, v113
	v_mul_f32_e32 v212, v251, v114
	v_mul_f32_e32 v213, v251, v115
	v_exp_f32_e32 v206, v206
	v_exp_f32_e32 v207, v207
	v_exp_f32_e32 v208, v208
	v_exp_f32_e32 v209, v209
	v_exp_f32_e32 v210, v210
	v_exp_f32_e32 v211, v211
	v_exp_f32_e32 v212, v212
	v_exp_f32_e32 v213, v213
	v_mul_f32_e32 v214, v120, v104
	v_mul_f32_e32 v215, v121, v105
	v_mul_f32_e32 v216, v122, v106
	v_mul_f32_e32 v217, v123, v107
	v_mul_f32_e32 v218, v112, v96
	v_mul_f32_e32 v219, v113, v97
	v_mul_f32_e32 v220, v114, v98
	v_mul_f32_e32 v221, v115, v99
	v_fma_f32 v206, v206, v243, v243
	v_fma_f32 v207, v207, v243, v243
	v_fma_f32 v208, v208, v243, v243
	v_fma_f32 v209, v209, v243, v243
	v_fma_f32 v210, v210, v243, v243
	v_fma_f32 v211, v211, v243, v243
	v_fma_f32 v212, v212, v243, v243
	v_fma_f32 v213, v213, v243, v243
	v_rcp_f32_e32 v206, v206
	v_rcp_f32_e32 v207, v207
	v_rcp_f32_e32 v208, v208
	v_rcp_f32_e32 v209, v209
	v_rcp_f32_e32 v210, v210
	v_rcp_f32_e32 v211, v211
	v_rcp_f32_e32 v212, v212
	v_rcp_f32_e32 v213, v213
	s_nop 0
	v_mul_f32_e32 v214, v214, v206
	v_mul_f32_e32 v215, v215, v207
	v_mul_f32_e32 v216, v216, v208
	v_mul_f32_e32 v217, v217, v209
	v_mul_f32_e32 v218, v218, v210
	v_mul_f32_e32 v219, v219, v211
	v_mul_f32_e32 v220, v220, v212
	v_mul_f32_e32 v221, v221, v213
	v_cvt_pk_bf16_f32 v206, v214, v215
	v_cvt_pk_bf16_f32 v207, v216, v217
	v_cvt_pk_bf16_f32 v208, v218, v219
	v_cvt_pk_bf16_f32 v209, v220, v221
	global_store_dwordx4 v[174:175], v[206:209], off nt
	v_lshl_add_u64 v[174:175], v[174:175], 0, s[78:79]
	v_mul_f32_e32 v190, v252, v92
	v_mul_f32_e32 v191, v252, v93
	v_mul_f32_e32 v192, v252, v94
	v_mul_f32_e32 v193, v252, v95
	v_mul_f32_e32 v194, v252, v84
	v_mul_f32_e32 v195, v252, v85
	v_mul_f32_e32 v196, v252, v86
	v_mul_f32_e32 v197, v252, v87
	v_exp_f32_e32 v190, v190
	v_exp_f32_e32 v191, v191
	v_exp_f32_e32 v192, v192
	v_exp_f32_e32 v193, v193
	v_exp_f32_e32 v194, v194
	v_exp_f32_e32 v195, v195
	v_exp_f32_e32 v196, v196
	v_exp_f32_e32 v197, v197
	v_mul_f32_e32 v198, v92, v76
	v_mul_f32_e32 v199, v93, v77
	v_mul_f32_e32 v200, v94, v78
	v_mul_f32_e32 v201, v95, v79
	v_mul_f32_e32 v202, v84, v68
	v_mul_f32_e32 v203, v85, v69
	v_mul_f32_e32 v204, v86, v70
	v_mul_f32_e32 v205, v87, v71
	v_fma_f32 v190, v190, v244, v244
	v_fma_f32 v191, v191, v244, v244
	v_fma_f32 v192, v192, v244, v244
	v_fma_f32 v193, v193, v244, v244
	v_fma_f32 v194, v194, v244, v244
	v_fma_f32 v195, v195, v244, v244
	v_fma_f32 v196, v196, v244, v244
	v_fma_f32 v197, v197, v244, v244
	v_rcp_f32_e32 v190, v190
	v_rcp_f32_e32 v191, v191
	v_rcp_f32_e32 v192, v192
	v_rcp_f32_e32 v193, v193
	v_rcp_f32_e32 v194, v194
	v_rcp_f32_e32 v195, v195
	v_rcp_f32_e32 v196, v196
	v_rcp_f32_e32 v197, v197
	s_nop 0
	v_mul_f32_e32 v198, v198, v190
	v_mul_f32_e32 v199, v199, v191
	v_mul_f32_e32 v200, v200, v192
	v_mul_f32_e32 v201, v201, v193
	v_mul_f32_e32 v202, v202, v194
	v_mul_f32_e32 v203, v203, v195
	v_mul_f32_e32 v204, v204, v196
	v_mul_f32_e32 v205, v205, v197
	v_cvt_pk_bf16_f32 v190, v198, v199
	v_cvt_pk_bf16_f32 v191, v200, v201
	v_cvt_pk_bf16_f32 v192, v202, v203
	v_cvt_pk_bf16_f32 v193, v204, v205
	global_store_dwordx4 v[174:175], v[190:193], off nt
	v_lshl_add_u64 v[174:175], v[174:175], 0, s[78:79]
	v_mul_f32_e32 v206, v253, v88
	v_mul_f32_e32 v207, v253, v89
	v_mul_f32_e32 v208, v253, v90
	v_mul_f32_e32 v209, v253, v91
	v_mul_f32_e32 v210, v253, v80
	v_mul_f32_e32 v211, v253, v81
	v_mul_f32_e32 v212, v253, v82
	v_mul_f32_e32 v213, v253, v83
	v_exp_f32_e32 v206, v206
	v_exp_f32_e32 v207, v207
	v_exp_f32_e32 v208, v208
	v_exp_f32_e32 v209, v209
	v_exp_f32_e32 v210, v210
	v_exp_f32_e32 v211, v211
	v_exp_f32_e32 v212, v212
	v_exp_f32_e32 v213, v213
	v_mul_f32_e32 v214, v88, v72
	v_mul_f32_e32 v215, v89, v73
	v_mul_f32_e32 v216, v90, v74
	v_mul_f32_e32 v217, v91, v75
	v_mul_f32_e32 v218, v80, v64
	v_mul_f32_e32 v219, v81, v65
	v_mul_f32_e32 v220, v82, v66
	v_mul_f32_e32 v221, v83, v67
	v_fma_f32 v206, v206, v245, v245
	v_fma_f32 v207, v207, v245, v245
	v_fma_f32 v208, v208, v245, v245
	v_fma_f32 v209, v209, v245, v245
	v_fma_f32 v210, v210, v245, v245
	v_fma_f32 v211, v211, v245, v245
	v_fma_f32 v212, v212, v245, v245
	v_fma_f32 v213, v213, v245, v245
	v_rcp_f32_e32 v206, v206
	v_rcp_f32_e32 v207, v207
	v_rcp_f32_e32 v208, v208
	v_rcp_f32_e32 v209, v209
	v_rcp_f32_e32 v210, v210
	v_rcp_f32_e32 v211, v211
	v_rcp_f32_e32 v212, v212
	v_rcp_f32_e32 v213, v213
	s_nop 0
	v_mul_f32_e32 v214, v214, v206
	v_mul_f32_e32 v215, v215, v207
	v_mul_f32_e32 v216, v216, v208
	v_mul_f32_e32 v217, v217, v209
	v_mul_f32_e32 v218, v218, v210
	v_mul_f32_e32 v219, v219, v211
	v_mul_f32_e32 v220, v220, v212
	v_mul_f32_e32 v221, v221, v213
	v_cvt_pk_bf16_f32 v206, v214, v215
	v_cvt_pk_bf16_f32 v207, v216, v217
	v_cvt_pk_bf16_f32 v208, v218, v219
	v_cvt_pk_bf16_f32 v209, v220, v221
	global_store_dwordx4 v[174:175], v[206:209], off nt
	v_mul_f32_e32 v190, v168, v60
	v_mul_f32_e32 v191, v168, v61
	v_mul_f32_e32 v192, v168, v62
	v_mul_f32_e32 v193, v168, v63
	v_mul_f32_e32 v194, v168, v56
	v_mul_f32_e32 v195, v168, v57
	v_mul_f32_e32 v196, v168, v58
	v_mul_f32_e32 v197, v168, v59
	v_exp_f32_e32 v190, v190
	v_exp_f32_e32 v191, v191
	v_exp_f32_e32 v192, v192
	v_exp_f32_e32 v193, v193
	v_exp_f32_e32 v194, v194
	v_exp_f32_e32 v195, v195
	v_exp_f32_e32 v196, v196
	v_exp_f32_e32 v197, v197
	v_mul_f32_e32 v198, v60, v44
	v_mul_f32_e32 v199, v61, v45
	v_mul_f32_e32 v200, v62, v46
	v_mul_f32_e32 v201, v63, v47
	v_mul_f32_e32 v202, v56, v36
	v_mul_f32_e32 v203, v57, v37
	v_mul_f32_e32 v204, v58, v38
	v_mul_f32_e32 v205, v59, v39
	v_fma_f32 v190, v190, v246, v246
	v_fma_f32 v191, v191, v246, v246
	v_fma_f32 v192, v192, v246, v246
	v_fma_f32 v193, v193, v246, v246
	v_fma_f32 v194, v194, v246, v246
	v_fma_f32 v195, v195, v246, v246
	v_fma_f32 v196, v196, v246, v246
	v_fma_f32 v197, v197, v246, v246
	v_rcp_f32_e32 v190, v190
	v_rcp_f32_e32 v191, v191
	v_rcp_f32_e32 v192, v192
	v_rcp_f32_e32 v193, v193
	v_rcp_f32_e32 v194, v194
	v_rcp_f32_e32 v195, v195
	v_rcp_f32_e32 v196, v196
	v_rcp_f32_e32 v197, v197
	s_nop 0
	v_mul_f32_e32 v198, v198, v190
	v_mul_f32_e32 v199, v199, v191
	v_mul_f32_e32 v200, v200, v192
	v_mul_f32_e32 v201, v201, v193
	v_mul_f32_e32 v202, v202, v194
	v_mul_f32_e32 v203, v203, v195
	v_mul_f32_e32 v204, v204, v196
	v_mul_f32_e32 v205, v205, v197
	v_cvt_pk_bf16_f32 v190, v198, v199
	v_cvt_pk_bf16_f32 v191, v200, v201
	v_cvt_pk_bf16_f32 v192, v202, v203
	v_cvt_pk_bf16_f32 v193, v204, v205
	global_store_dwordx4 v[166:167], v[190:193], off nt
	v_lshl_add_u64 v[166:167], v[166:167], 0, s[78:79]
	v_mul_f32_e32 v206, v170, v52
	v_mul_f32_e32 v207, v170, v53
	v_mul_f32_e32 v208, v170, v54
	v_mul_f32_e32 v209, v170, v55
	v_mul_f32_e32 v210, v170, v48
	v_mul_f32_e32 v211, v170, v49
	v_mul_f32_e32 v212, v170, v50
	v_mul_f32_e32 v213, v170, v51
	v_exp_f32_e32 v206, v206
	v_exp_f32_e32 v207, v207
	v_exp_f32_e32 v208, v208
	v_exp_f32_e32 v209, v209
	v_exp_f32_e32 v210, v210
	v_exp_f32_e32 v211, v211
	v_exp_f32_e32 v212, v212
	v_exp_f32_e32 v213, v213
	v_mul_f32_e32 v214, v52, v40
	v_mul_f32_e32 v215, v53, v41
	v_mul_f32_e32 v216, v54, v42
	v_mul_f32_e32 v217, v55, v43
	v_mul_f32_e32 v218, v48, v32
	v_mul_f32_e32 v219, v49, v33
	v_mul_f32_e32 v220, v50, v34
	v_mul_f32_e32 v221, v51, v35
	v_fma_f32 v206, v206, v247, v247
	v_fma_f32 v207, v207, v247, v247
	v_fma_f32 v208, v208, v247, v247
	v_fma_f32 v209, v209, v247, v247
	v_fma_f32 v210, v210, v247, v247
	v_fma_f32 v211, v211, v247, v247
	v_fma_f32 v212, v212, v247, v247
	v_fma_f32 v213, v213, v247, v247
	v_rcp_f32_e32 v206, v206
	v_rcp_f32_e32 v207, v207
	v_rcp_f32_e32 v208, v208
	v_rcp_f32_e32 v209, v209
	v_rcp_f32_e32 v210, v210
	v_rcp_f32_e32 v211, v211
	v_rcp_f32_e32 v212, v212
	v_rcp_f32_e32 v213, v213
	s_nop 0
	v_mul_f32_e32 v214, v214, v206
	v_mul_f32_e32 v215, v215, v207
	v_mul_f32_e32 v216, v216, v208
	v_mul_f32_e32 v217, v217, v209
	v_mul_f32_e32 v218, v218, v210
	v_mul_f32_e32 v219, v219, v211
	v_mul_f32_e32 v220, v220, v212
	v_mul_f32_e32 v221, v221, v213
	v_cvt_pk_bf16_f32 v206, v214, v215
	v_cvt_pk_bf16_f32 v207, v216, v217
	v_cvt_pk_bf16_f32 v208, v218, v219
	v_cvt_pk_bf16_f32 v209, v220, v221
	global_store_dwordx4 v[166:167], v[206:209], off nt
	v_lshl_add_u64 v[166:167], v[166:167], 0, s[78:79]
	v_mul_f32_e32 v190, v176, v28
	v_mul_f32_e32 v191, v176, v29
	v_mul_f32_e32 v192, v176, v30
	v_mul_f32_e32 v193, v176, v31
	v_mul_f32_e32 v194, v176, v20
	v_mul_f32_e32 v195, v176, v21
	v_mul_f32_e32 v196, v176, v22
	v_mul_f32_e32 v197, v176, v23
	v_exp_f32_e32 v190, v190
	v_exp_f32_e32 v191, v191
	v_exp_f32_e32 v192, v192
	v_exp_f32_e32 v193, v193
	v_exp_f32_e32 v194, v194
	v_exp_f32_e32 v195, v195
	v_exp_f32_e32 v196, v196
	v_exp_f32_e32 v197, v197
	v_mul_f32_e32 v198, v28, v12
	v_mul_f32_e32 v199, v29, v13
	v_mul_f32_e32 v200, v30, v14
	v_mul_f32_e32 v201, v31, v15
	v_mul_f32_e32 v202, v20, v4
	v_mul_f32_e32 v203, v21, v5
	v_mul_f32_e32 v204, v22, v6
	v_mul_f32_e32 v205, v23, v7
	v_fma_f32 v190, v190, v248, v248
	v_fma_f32 v191, v191, v248, v248
	v_fma_f32 v192, v192, v248, v248
	v_fma_f32 v193, v193, v248, v248
	v_fma_f32 v194, v194, v248, v248
	v_fma_f32 v195, v195, v248, v248
	v_fma_f32 v196, v196, v248, v248
	v_fma_f32 v197, v197, v248, v248
	v_rcp_f32_e32 v190, v190
	v_rcp_f32_e32 v191, v191
	v_rcp_f32_e32 v192, v192
	v_rcp_f32_e32 v193, v193
	v_rcp_f32_e32 v194, v194
	v_rcp_f32_e32 v195, v195
	v_rcp_f32_e32 v196, v196
	v_rcp_f32_e32 v197, v197
	s_nop 0
	v_mul_f32_e32 v198, v198, v190
	v_mul_f32_e32 v199, v199, v191
	v_mul_f32_e32 v200, v200, v192
	v_mul_f32_e32 v201, v201, v193
	v_mul_f32_e32 v202, v202, v194
	v_mul_f32_e32 v203, v203, v195
	v_mul_f32_e32 v204, v204, v196
	v_mul_f32_e32 v205, v205, v197
	v_cvt_pk_bf16_f32 v190, v198, v199
	v_cvt_pk_bf16_f32 v191, v200, v201
	v_cvt_pk_bf16_f32 v192, v202, v203
	v_cvt_pk_bf16_f32 v193, v204, v205
	global_store_dwordx4 v[166:167], v[190:193], off nt
	v_lshl_add_u64 v[166:167], v[166:167], 0, s[78:79]
	v_mul_f32_e32 v206, v178, v24
	v_mul_f32_e32 v207, v178, v25
	v_mul_f32_e32 v208, v178, v26
	v_mul_f32_e32 v209, v178, v27
	v_mul_f32_e32 v210, v178, v16
	v_mul_f32_e32 v211, v178, v17
	v_mul_f32_e32 v212, v178, v18
	v_mul_f32_e32 v213, v178, v19
	v_exp_f32_e32 v206, v206
	v_exp_f32_e32 v207, v207
	v_exp_f32_e32 v208, v208
	v_exp_f32_e32 v209, v209
	v_exp_f32_e32 v210, v210
	v_exp_f32_e32 v211, v211
	v_exp_f32_e32 v212, v212
	v_exp_f32_e32 v213, v213
	v_mul_f32_e32 v214, v24, v8
	v_mul_f32_e32 v215, v25, v9
	v_mul_f32_e32 v216, v26, v10
	v_mul_f32_e32 v217, v27, v11
	v_mul_f32_e32 v218, v16, v0
	v_mul_f32_e32 v219, v17, v1
	v_mul_f32_e32 v220, v18, v2
	v_mul_f32_e32 v221, v19, v3
	v_fma_f32 v206, v206, v249, v249
	v_fma_f32 v207, v207, v249, v249
	v_fma_f32 v208, v208, v249, v249
	v_fma_f32 v209, v209, v249, v249
	v_fma_f32 v210, v210, v249, v249
	v_fma_f32 v211, v211, v249, v249
	v_fma_f32 v212, v212, v249, v249
	v_fma_f32 v213, v213, v249, v249
	v_rcp_f32_e32 v206, v206
	v_rcp_f32_e32 v207, v207
	v_rcp_f32_e32 v208, v208
	v_rcp_f32_e32 v209, v209
	v_rcp_f32_e32 v210, v210
	v_rcp_f32_e32 v211, v211
	v_rcp_f32_e32 v212, v212
	v_rcp_f32_e32 v213, v213
	s_nop 0
	v_mul_f32_e32 v214, v214, v206
	v_mul_f32_e32 v215, v215, v207
	v_mul_f32_e32 v216, v216, v208
	v_mul_f32_e32 v217, v217, v209
	v_mul_f32_e32 v218, v218, v210
	v_mul_f32_e32 v219, v219, v211
	v_mul_f32_e32 v220, v220, v212
	v_mul_f32_e32 v221, v221, v213
	v_cvt_pk_bf16_f32 v206, v214, v215
	v_cvt_pk_bf16_f32 v207, v216, v217
	v_cvt_pk_bf16_f32 v208, v218, v219
	v_cvt_pk_bf16_f32 v209, v220, v221
	global_store_dwordx4 v[166:167], v[206:209], off nt
	s_branch .LBB0_514
